# final candidate + accumulator zeroing with v_pk_mov_b32 (64 instead of 128 VALU per unit)
# speedup vs baseline: 1.0122x; 1.0117x over previous
.LBB0_189:
	s_add_u32 s66, s66, 0x100
	s_addc_u32 s67, s67, 0
	s_add_u32 s64, s64, 0x40080
	v_mov_b32_e32 v2, 0
	s_addc_u32 s65, s65, 0
	s_mov_b32 s68, -2
	v_mov_b32_e32 v3, 0
	v_pk_mov_b32 v[4:5], v[2:3], v[2:3]
	v_pk_mov_b32 v[6:7], v[2:3], v[2:3]
	v_pk_mov_b32 v[8:9], v[2:3], v[2:3]
	v_pk_mov_b32 v[10:11], v[2:3], v[2:3]
	v_pk_mov_b32 v[12:13], v[2:3], v[2:3]
	v_pk_mov_b32 v[14:15], v[2:3], v[2:3]
	v_pk_mov_b32 v[16:17], v[2:3], v[2:3]
	v_pk_mov_b32 v[18:19], v[2:3], v[2:3]
	v_pk_mov_b32 v[20:21], v[2:3], v[2:3]
	v_pk_mov_b32 v[22:23], v[2:3], v[2:3]
	v_pk_mov_b32 v[24:25], v[2:3], v[2:3]
	v_pk_mov_b32 v[26:27], v[2:3], v[2:3]
	v_pk_mov_b32 v[28:29], v[2:3], v[2:3]
	v_pk_mov_b32 v[30:31], v[2:3], v[2:3]
	v_pk_mov_b32 v[32:33], v[2:3], v[2:3]
	v_pk_mov_b32 v[34:35], v[2:3], v[2:3]
	v_pk_mov_b32 v[36:37], v[2:3], v[2:3]
	v_pk_mov_b32 v[38:39], v[2:3], v[2:3]
	v_pk_mov_b32 v[40:41], v[2:3], v[2:3]
	v_pk_mov_b32 v[42:43], v[2:3], v[2:3]
	v_pk_mov_b32 v[44:45], v[2:3], v[2:3]
	v_pk_mov_b32 v[46:47], v[2:3], v[2:3]
	v_pk_mov_b32 v[48:49], v[2:3], v[2:3]
	v_pk_mov_b32 v[50:51], v[2:3], v[2:3]
	v_pk_mov_b32 v[52:53], v[2:3], v[2:3]
	v_pk_mov_b32 v[54:55], v[2:3], v[2:3]
	v_pk_mov_b32 v[56:57], v[2:3], v[2:3]
	v_pk_mov_b32 v[58:59], v[2:3], v[2:3]
	v_pk_mov_b32 v[60:61], v[2:3], v[2:3]
	v_pk_mov_b32 v[62:63], v[2:3], v[2:3]
	v_pk_mov_b32 v[64:65], v[2:3], v[2:3]
	v_pk_mov_b32 v[66:67], v[2:3], v[2:3]
	v_pk_mov_b32 v[68:69], v[2:3], v[2:3]
	v_pk_mov_b32 v[70:71], v[2:3], v[2:3]
	v_pk_mov_b32 v[72:73], v[2:3], v[2:3]
	v_pk_mov_b32 v[74:75], v[2:3], v[2:3]
	v_pk_mov_b32 v[76:77], v[2:3], v[2:3]
	v_pk_mov_b32 v[78:79], v[2:3], v[2:3]
	v_pk_mov_b32 v[80:81], v[2:3], v[2:3]
	v_pk_mov_b32 v[82:83], v[2:3], v[2:3]
	v_pk_mov_b32 v[84:85], v[2:3], v[2:3]
	v_pk_mov_b32 v[86:87], v[2:3], v[2:3]
	v_pk_mov_b32 v[88:89], v[2:3], v[2:3]
	v_pk_mov_b32 v[90:91], v[2:3], v[2:3]
	v_pk_mov_b32 v[92:93], v[2:3], v[2:3]
	v_pk_mov_b32 v[94:95], v[2:3], v[2:3]
	v_pk_mov_b32 v[96:97], v[2:3], v[2:3]
	v_pk_mov_b32 v[98:99], v[2:3], v[2:3]
	v_pk_mov_b32 v[100:101], v[2:3], v[2:3]
	v_pk_mov_b32 v[102:103], v[2:3], v[2:3]
	v_pk_mov_b32 v[104:105], v[2:3], v[2:3]
	v_pk_mov_b32 v[106:107], v[2:3], v[2:3]
	v_pk_mov_b32 v[108:109], v[2:3], v[2:3]
	v_pk_mov_b32 v[110:111], v[2:3], v[2:3]
	v_pk_mov_b32 v[112:113], v[2:3], v[2:3]
	v_pk_mov_b32 v[114:115], v[2:3], v[2:3]
	v_pk_mov_b32 v[116:117], v[2:3], v[2:3]
	v_pk_mov_b32 v[118:119], v[2:3], v[2:3]
	v_pk_mov_b32 v[120:121], v[2:3], v[2:3]
	v_pk_mov_b32 v[122:123], v[2:3], v[2:3]
	v_pk_mov_b32 v[124:125], v[2:3], v[2:3]
	v_pk_mov_b32 v[126:127], v[2:3], v[2:3]
	v_pk_mov_b32 v[128:129], v[2:3], v[2:3]

.LBB0_1048:
	s_add_u32 s38, s68, 0x100
	s_addc_u32 s68, s69, 0
	s_add_u32 s66, s66, 0x40080
	v_mov_b32_e32 v2, 0
	s_addc_u32 s67, s67, 0
	s_mov_b32 s69, -2
	v_mov_b32_e32 v3, 0
	v_pk_mov_b32 v[4:5], v[2:3], v[2:3]
	v_pk_mov_b32 v[6:7], v[2:3], v[2:3]
	v_pk_mov_b32 v[8:9], v[2:3], v[2:3]
	v_pk_mov_b32 v[10:11], v[2:3], v[2:3]
	v_pk_mov_b32 v[12:13], v[2:3], v[2:3]
	v_pk_mov_b32 v[14:15], v[2:3], v[2:3]
	v_pk_mov_b32 v[16:17], v[2:3], v[2:3]
	v_pk_mov_b32 v[18:19], v[2:3], v[2:3]
	v_pk_mov_b32 v[20:21], v[2:3], v[2:3]
	v_pk_mov_b32 v[22:23], v[2:3], v[2:3]
	v_pk_mov_b32 v[24:25], v[2:3], v[2:3]
	v_pk_mov_b32 v[26:27], v[2:3], v[2:3]
	v_pk_mov_b32 v[28:29], v[2:3], v[2:3]
	v_pk_mov_b32 v[30:31], v[2:3], v[2:3]
	v_pk_mov_b32 v[32:33], v[2:3], v[2:3]
	v_pk_mov_b32 v[34:35], v[2:3], v[2:3]
	v_pk_mov_b32 v[36:37], v[2:3], v[2:3]
	v_pk_mov_b32 v[38:39], v[2:3], v[2:3]
	v_pk_mov_b32 v[40:41], v[2:3], v[2:3]
	v_pk_mov_b32 v[42:43], v[2:3], v[2:3]
	v_pk_mov_b32 v[44:45], v[2:3], v[2:3]
	v_pk_mov_b32 v[46:47], v[2:3], v[2:3]
	v_pk_mov_b32 v[48:49], v[2:3], v[2:3]
	v_pk_mov_b32 v[50:51], v[2:3], v[2:3]
	v_pk_mov_b32 v[52:53], v[2:3], v[2:3]
	v_pk_mov_b32 v[54:55], v[2:3], v[2:3]
	v_pk_mov_b32 v[56:57], v[2:3], v[2:3]
	v_pk_mov_b32 v[58:59], v[2:3], v[2:3]
	v_pk_mov_b32 v[60:61], v[2:3], v[2:3]
	v_pk_mov_b32 v[62:63], v[2:3], v[2:3]
	v_pk_mov_b32 v[64:65], v[2:3], v[2:3]
	v_pk_mov_b32 v[66:67], v[2:3], v[2:3]
	v_pk_mov_b32 v[68:69], v[2:3], v[2:3]
	v_pk_mov_b32 v[70:71], v[2:3], v[2:3]
	v_pk_mov_b32 v[72:73], v[2:3], v[2:3]
	v_pk_mov_b32 v[74:75], v[2:3], v[2:3]
	v_pk_mov_b32 v[76:77], v[2:3], v[2:3]
	v_pk_mov_b32 v[78:79], v[2:3], v[2:3]
	v_pk_mov_b32 v[80:81], v[2:3], v[2:3]
	v_pk_mov_b32 v[82:83], v[2:3], v[2:3]
	v_pk_mov_b32 v[84:85], v[2:3], v[2:3]
	v_pk_mov_b32 v[86:87], v[2:3], v[2:3]
	v_pk_mov_b32 v[88:89], v[2:3], v[2:3]
	v_pk_mov_b32 v[90:91], v[2:3], v[2:3]
	v_pk_mov_b32 v[92:93], v[2:3], v[2:3]
	v_pk_mov_b32 v[94:95], v[2:3], v[2:3]
	v_pk_mov_b32 v[96:97], v[2:3], v[2:3]
	v_pk_mov_b32 v[98:99], v[2:3], v[2:3]
	v_pk_mov_b32 v[100:101], v[2:3], v[2:3]
	v_pk_mov_b32 v[102:103], v[2:3], v[2:3]
	v_pk_mov_b32 v[104:105], v[2:3], v[2:3]
	v_pk_mov_b32 v[106:107], v[2:3], v[2:3]
	v_pk_mov_b32 v[108:109], v[2:3], v[2:3]
	v_pk_mov_b32 v[110:111], v[2:3], v[2:3]
	v_pk_mov_b32 v[112:113], v[2:3], v[2:3]
	v_pk_mov_b32 v[114:115], v[2:3], v[2:3]
	v_pk_mov_b32 v[116:117], v[2:3], v[2:3]
	v_pk_mov_b32 v[118:119], v[2:3], v[2:3]
	v_pk_mov_b32 v[120:121], v[2:3], v[2:3]
	v_pk_mov_b32 v[122:123], v[2:3], v[2:3]
	v_pk_mov_b32 v[124:125], v[2:3], v[2:3]
	v_pk_mov_b32 v[126:127], v[2:3], v[2:3]
	v_pk_mov_b32 v[128:129], v[2:3], v[2:3]

.LBB0_1630:
	s_add_u32 s62, s62, 0x100
	s_addc_u32 s63, s63, 0
	s_add_u32 s60, s60, 0x40080
	v_mov_b32_e32 v2, 0
	s_addc_u32 s61, s61, 0
	s_mov_b32 s79, -2
	v_mov_b32_e32 v3, 0
	v_pk_mov_b32 v[4:5], v[2:3], v[2:3]
	v_pk_mov_b32 v[6:7], v[2:3], v[2:3]
	v_pk_mov_b32 v[8:9], v[2:3], v[2:3]
	v_pk_mov_b32 v[10:11], v[2:3], v[2:3]
	v_pk_mov_b32 v[12:13], v[2:3], v[2:3]
	v_pk_mov_b32 v[14:15], v[2:3], v[2:3]
	v_pk_mov_b32 v[16:17], v[2:3], v[2:3]
	v_pk_mov_b32 v[18:19], v[2:3], v[2:3]
	v_pk_mov_b32 v[20:21], v[2:3], v[2:3]
	v_pk_mov_b32 v[22:23], v[2:3], v[2:3]
	v_pk_mov_b32 v[24:25], v[2:3], v[2:3]
	v_pk_mov_b32 v[26:27], v[2:3], v[2:3]
	v_pk_mov_b32 v[28:29], v[2:3], v[2:3]
	v_pk_mov_b32 v[30:31], v[2:3], v[2:3]
	v_pk_mov_b32 v[32:33], v[2:3], v[2:3]
	v_pk_mov_b32 v[34:35], v[2:3], v[2:3]
	v_pk_mov_b32 v[36:37], v[2:3], v[2:3]
	v_pk_mov_b32 v[38:39], v[2:3], v[2:3]
	v_pk_mov_b32 v[40:41], v[2:3], v[2:3]
	v_pk_mov_b32 v[42:43], v[2:3], v[2:3]
	v_pk_mov_b32 v[44:45], v[2:3], v[2:3]
	v_pk_mov_b32 v[46:47], v[2:3], v[2:3]
	v_pk_mov_b32 v[48:49], v[2:3], v[2:3]
	v_pk_mov_b32 v[50:51], v[2:3], v[2:3]
	v_pk_mov_b32 v[52:53], v[2:3], v[2:3]
	v_pk_mov_b32 v[54:55], v[2:3], v[2:3]
	v_pk_mov_b32 v[56:57], v[2:3], v[2:3]
	v_pk_mov_b32 v[58:59], v[2:3], v[2:3]
	v_pk_mov_b32 v[60:61], v[2:3], v[2:3]
	v_pk_mov_b32 v[62:63], v[2:3], v[2:3]
	v_pk_mov_b32 v[64:65], v[2:3], v[2:3]
	v_pk_mov_b32 v[66:67], v[2:3], v[2:3]
	v_pk_mov_b32 v[68:69], v[2:3], v[2:3]
	v_pk_mov_b32 v[70:71], v[2:3], v[2:3]
	v_pk_mov_b32 v[72:73], v[2:3], v[2:3]
	v_pk_mov_b32 v[74:75], v[2:3], v[2:3]
	v_pk_mov_b32 v[76:77], v[2:3], v[2:3]
	v_pk_mov_b32 v[78:79], v[2:3], v[2:3]
	v_pk_mov_b32 v[80:81], v[2:3], v[2:3]
	v_pk_mov_b32 v[82:83], v[2:3], v[2:3]
	v_pk_mov_b32 v[84:85], v[2:3], v[2:3]
	v_pk_mov_b32 v[86:87], v[2:3], v[2:3]
	v_pk_mov_b32 v[88:89], v[2:3], v[2:3]
	v_pk_mov_b32 v[90:91], v[2:3], v[2:3]
	v_pk_mov_b32 v[92:93], v[2:3], v[2:3]
	v_pk_mov_b32 v[94:95], v[2:3], v[2:3]
	v_pk_mov_b32 v[96:97], v[2:3], v[2:3]
	v_pk_mov_b32 v[98:99], v[2:3], v[2:3]
	v_pk_mov_b32 v[100:101], v[2:3], v[2:3]
	v_pk_mov_b32 v[102:103], v[2:3], v[2:3]
	v_pk_mov_b32 v[104:105], v[2:3], v[2:3]
	v_pk_mov_b32 v[106:107], v[2:3], v[2:3]
	v_pk_mov_b32 v[108:109], v[2:3], v[2:3]
	v_pk_mov_b32 v[110:111], v[2:3], v[2:3]
	v_pk_mov_b32 v[112:113], v[2:3], v[2:3]
	v_pk_mov_b32 v[114:115], v[2:3], v[2:3]
	v_pk_mov_b32 v[116:117], v[2:3], v[2:3]
	v_pk_mov_b32 v[118:119], v[2:3], v[2:3]
	v_pk_mov_b32 v[120:121], v[2:3], v[2:3]
	v_pk_mov_b32 v[126:127], v[2:3], v[2:3]
	v_pk_mov_b32 v[128:129], v[2:3], v[2:3]
	v_pk_mov_b32 v[130:131], v[2:3], v[2:3]
	v_pk_mov_b32 v[132:133], v[2:3], v[2:3]

.LBB0_1705:
	s_add_u32 s62, s62, 0x100
	s_addc_u32 s63, s63, 0
	s_add_u32 s60, s60, 0x40080
	v_mov_b32_e32 v2, 0
	s_addc_u32 s61, s61, 0
	s_mov_b32 s86, -2
	v_mov_b32_e32 v3, 0
	v_pk_mov_b32 v[4:5], v[2:3], v[2:3]
	v_pk_mov_b32 v[6:7], v[2:3], v[2:3]
	v_pk_mov_b32 v[8:9], v[2:3], v[2:3]
	v_pk_mov_b32 v[10:11], v[2:3], v[2:3]
	v_pk_mov_b32 v[12:13], v[2:3], v[2:3]
	v_pk_mov_b32 v[14:15], v[2:3], v[2:3]
	v_pk_mov_b32 v[16:17], v[2:3], v[2:3]
	v_pk_mov_b32 v[18:19], v[2:3], v[2:3]
	v_pk_mov_b32 v[20:21], v[2:3], v[2:3]
	v_pk_mov_b32 v[22:23], v[2:3], v[2:3]
	v_pk_mov_b32 v[24:25], v[2:3], v[2:3]
	v_pk_mov_b32 v[26:27], v[2:3], v[2:3]
	v_pk_mov_b32 v[28:29], v[2:3], v[2:3]
	v_pk_mov_b32 v[30:31], v[2:3], v[2:3]
	v_pk_mov_b32 v[32:33], v[2:3], v[2:3]
	v_pk_mov_b32 v[34:35], v[2:3], v[2:3]
	v_pk_mov_b32 v[36:37], v[2:3], v[2:3]
	v_pk_mov_b32 v[38:39], v[2:3], v[2:3]
	v_pk_mov_b32 v[40:41], v[2:3], v[2:3]
	v_pk_mov_b32 v[42:43], v[2:3], v[2:3]
	v_pk_mov_b32 v[44:45], v[2:3], v[2:3]
	v_pk_mov_b32 v[46:47], v[2:3], v[2:3]
	v_pk_mov_b32 v[48:49], v[2:3], v[2:3]
	v_pk_mov_b32 v[50:51], v[2:3], v[2:3]
	v_pk_mov_b32 v[52:53], v[2:3], v[2:3]
	v_pk_mov_b32 v[54:55], v[2:3], v[2:3]
	v_pk_mov_b32 v[56:57], v[2:3], v[2:3]
	v_pk_mov_b32 v[58:59], v[2:3], v[2:3]
	v_pk_mov_b32 v[60:61], v[2:3], v[2:3]
	v_pk_mov_b32 v[62:63], v[2:3], v[2:3]
	v_pk_mov_b32 v[64:65], v[2:3], v[2:3]
	v_pk_mov_b32 v[66:67], v[2:3], v[2:3]
	v_pk_mov_b32 v[68:69], v[2:3], v[2:3]
	v_pk_mov_b32 v[70:71], v[2:3], v[2:3]
	v_pk_mov_b32 v[72:73], v[2:3], v[2:3]
	v_pk_mov_b32 v[74:75], v[2:3], v[2:3]
	v_pk_mov_b32 v[76:77], v[2:3], v[2:3]
	v_pk_mov_b32 v[78:79], v[2:3], v[2:3]
	v_pk_mov_b32 v[80:81], v[2:3], v[2:3]
	v_pk_mov_b32 v[82:83], v[2:3], v[2:3]
	v_pk_mov_b32 v[84:85], v[2:3], v[2:3]
	v_pk_mov_b32 v[86:87], v[2:3], v[2:3]
	v_pk_mov_b32 v[88:89], v[2:3], v[2:3]
	v_pk_mov_b32 v[90:91], v[2:3], v[2:3]
	v_pk_mov_b32 v[92:93], v[2:3], v[2:3]
	v_pk_mov_b32 v[94:95], v[2:3], v[2:3]
	v_pk_mov_b32 v[96:97], v[2:3], v[2:3]
	v_pk_mov_b32 v[98:99], v[2:3], v[2:3]
	v_pk_mov_b32 v[100:101], v[2:3], v[2:3]
	v_pk_mov_b32 v[102:103], v[2:3], v[2:3]
	v_pk_mov_b32 v[104:105], v[2:3], v[2:3]
	v_pk_mov_b32 v[106:107], v[2:3], v[2:3]
	v_pk_mov_b32 v[108:109], v[2:3], v[2:3]
	v_pk_mov_b32 v[110:111], v[2:3], v[2:3]
	v_pk_mov_b32 v[112:113], v[2:3], v[2:3]
	v_pk_mov_b32 v[114:115], v[2:3], v[2:3]
	v_pk_mov_b32 v[116:117], v[2:3], v[2:3]
	v_pk_mov_b32 v[118:119], v[2:3], v[2:3]
	v_pk_mov_b32 v[120:121], v[2:3], v[2:3]
	v_pk_mov_b32 v[122:123], v[2:3], v[2:3]
	v_pk_mov_b32 v[124:125], v[2:3], v[2:3]
	v_pk_mov_b32 v[126:127], v[2:3], v[2:3]
	v_pk_mov_b32 v[128:129], v[2:3], v[2:3]
